# fox_prompt softmax: row-max tree rewritten as two v_max3 chains (17 VALU instead of 53, no canonicalising self-max)
# speedup vs baseline: 1.0074x; 1.0019x over previous
; #define LAS __attribute__((address_space(3)))
; __device__ __forceinline__ unsigned pkbf(float lo, float hi) { f32x2 v = {lo, hi}; bf16x2_t b = __builtin_convertvector(v, bf16x2_t); return __builtin_bit_cast(unsigned, b); }
; __device__ __forceinline__ s16x4 lds_tr(LAS const char* p) { return __builtin_bit_cast(s16x4, __builtin_amdgcn_ds_read_tr16_b64_v4i16((LAS s16x4*)p)); }
; __device__ __forceinline__ bf16x8 cat44(s16x4 a, s16x4 b) { return (bf16x8){a[0], a[1], a[2], a[3], b[0], b[1], b[2], b[3]}; }
; __device__ __forceinline__ float fexp2(float x) { return __builtin_amdgcn_exp2f(x); }
; __device__ __forceinline__ void fox_prompt_unit(LAS char* L, const bf16_t* P, const float* lfT, bf16_t* MIX, int b, int h, int qb, const int wv) {
;     ...
;             float mx = fmaxf(s0[0], s1[0]);
; #pragma unroll
;             for (int r = 1; r < 16; ++r) mx = fmaxf(mx, fmaxf(s0[r], s1[r]));
;             mx = xmax32(mx);
;             const float mn = fmaxf(m, mx), alpha = fexp2(m - mn); m = mn;
;             float ls = 0.f;
; #pragma unroll
;             for (int r = 0; r < 16; ++r) { s0[r] = fexp2(s0[r] - mn); s1[r] = fexp2(s1[r] - mn); ls += s0[r] + s1[r]; }
;             l = l * alpha + ls;
; #pragma unroll
;             for (int d = 0; d < 4; ++d)
; #pragma unroll
;                 for (int r = 0; r < 16; ++r) o[d][r] *= alpha;
;             bf16x8 pf[4];
;             { u32x4 w;
;               w.x = pkbf(s0[0], s0[1]); w.y = pkbf(s0[2], s0[3]); w.z = pkbf(s0[4], s0[5]); w.w = pkbf(s0[6], s0[7]); pf[0] = __builtin_bit_cast(bf16x8, w);
;               w.x = pkbf(s0[8], s0[9]); w.y = pkbf(s0[10], s0[11]); w.z = pkbf(s0[12], s0[13]); w.w = pkbf(s0[14], s0[15]); pf[1] = __builtin_bit_cast(bf16x8, w);
;               w.x = pkbf(s1[0], s1[1]); w.y = pkbf(s1[2], s1[3]); w.z = pkbf(s1[4], s1[5]); w.w = pkbf(s1[6], s1[7]); pf[2] = __builtin_bit_cast(bf16x8, w);
;               w.x = pkbf(s1[8], s1[9]); w.y = pkbf(s1[10], s1[11]); w.z = pkbf(s1[12], s1[13]); w.w = pkbf(s1[14], s1[15]); pf[3] = __builtin_bit_cast(bf16x8, w); }
; #pragma unroll
;             for (int ss = 0; ss < 4; ++ss)
; #pragma unroll
;                 for (int d = 0; d < 4; ++d) { LAS const char* vp = Vb + (16 * ss + 4 * hi + (i16 >> 2)) * AVP + (32 * d + 16 * cb + 4 * (i16 & 3)) * 2;
;                     o[d] = mfma32(cat44(lds_tr(vp), lds_tr(vp + 8 * AVP)), pf[ss], o[d]); }
.LBB0_202:
	s_mulk_i32 s17, 0x5000
	v_add_u32_e32 v248, s17, v172
	ds_read_b64_tr_b16 v[200:201], v248 offset:34816
	ds_read_b64_tr_b16 v[202:203], v248 offset:37376
	ds_read_b64_tr_b16 v[204:205], v248 offset:34880
	ds_read_b64_tr_b16 v[206:207], v248 offset:37440
	ds_read_b64_tr_b16 v[208:209], v248 offset:34944
	ds_read_b64_tr_b16 v[210:211], v248 offset:37504
	ds_read_b64_tr_b16 v[212:213], v248 offset:35008
	ds_read_b64_tr_b16 v[214:215], v248 offset:37568
	ds_read_b64_tr_b16 v[216:217], v248 offset:39936
	ds_read_b64_tr_b16 v[218:219], v248 offset:42496
	ds_read_b64_tr_b16 v[220:221], v248 offset:40000
	ds_read_b64_tr_b16 v[222:223], v248 offset:42560
	s_nop 5
	v_max3_f32 v0, v66, v67, v68
	v_max3_f32 v146, v82, v83, v84
	v_max3_f32 v0, v0, v69, v70
	v_max3_f32 v146, v146, v85, v86
	v_max3_f32 v0, v0, v71, v72
	v_max3_f32 v146, v146, v87, v88
	v_max3_f32 v0, v0, v73, v74
	v_max3_f32 v146, v146, v89, v90
	v_max3_f32 v0, v0, v75, v76
	v_max3_f32 v146, v146, v91, v92
	v_max3_f32 v0, v0, v77, v78
	v_max3_f32 v146, v146, v93, v94
	v_max3_f32 v0, v0, v79, v80
	v_max3_f32 v146, v146, v95, v96
	v_max_f32_e32 v0, v81, v0
	v_max_f32_e32 v146, v97, v146
	v_max_f32_e32 v0, v146, v0
	v_mov_b32_e32 v146, v0
	ds_read_b64_tr_b16 v[224:225], v248 offset:40064
	ds_read_b64_tr_b16 v[226:227], v248 offset:42624
	ds_read_b64_tr_b16 v[228:229], v248 offset:40128
	ds_read_b64_tr_b16 v[230:231], v248 offset:42688
	ds_read_b64_tr_b16 v[232:233], v248 offset:45056
	ds_read_b64_tr_b16 v[234:235], v248 offset:47616
	ds_read_b64_tr_b16 v[236:237], v248 offset:45120
	ds_read_b64_tr_b16 v[238:239], v248 offset:47680
	ds_read_b64_tr_b16 v[240:241], v248 offset:45248
	ds_read_b64_tr_b16 v[242:243], v248 offset:47808
	ds_read_b64_tr_b16 v[244:245], v248 offset:45184
	ds_read_b64_tr_b16 v[246:247], v248 offset:47744
	s_nop 1
	v_permlane32_swap_b32_e32 v0, v146
	v_max3_f32 v178, v158, v0, v146
	v_sub_f32_e32 v0, v82, v178
	v_sub_f32_e32 v68, v68, v178
	v_exp_f32_e32 v146, v0
	v_sub_f32_e32 v0, v66, v178
	v_sub_f32_e32 v82, v84, v178
	v_exp_f32_e32 v179, v68
	v_sub_f32_e32 v68, v87, v178
	v_exp_f32_e32 v163, v0
	v_sub_f32_e32 v0, v83, v178
	v_exp_f32_e32 v147, v82
	v_exp_f32_e32 v82, v68
	v_sub_f32_e32 v68, v88, v178
	v_sub_f32_e32 v66, v158, v178
	v_exp_f32_e32 v158, v0
	v_sub_f32_e32 v0, v67, v178
	v_sub_f32_e32 v67, v85, v178
	v_exp_f32_e32 v85, v68
	v_sub_f32_e32 v68, v72, v178
	v_exp_f32_e32 v160, v67
	v_sub_f32_e32 v67, v69, v178
	v_exp_f32_e32 v69, v68
	v_sub_f32_e32 v68, v89, v178
	v_exp_f32_e32 v84, v68
	v_sub_f32_e32 v68, v90, v178
	v_exp_f32_e32 v162, v67
	v_sub_f32_e32 v67, v86, v178
	v_exp_f32_e32 v190, v68
	v_sub_f32_e32 v68, v91, v178
	v_exp_f32_e32 v83, v67
	v_sub_f32_e32 v67, v70, v178
	v_exp_f32_e32 v70, v68
	v_sub_f32_e32 v68, v92, v178
	v_exp_f32_e32 v91, v68
	v_sub_f32_e32 v68, v93, v178
	v_exp_f32_e32 v72, v68
	v_sub_f32_e32 v68, v94, v178
	v_sub_f32_e32 v86, v96, v178
	v_add_u32_e32 v92, s17, v172
	v_exp_f32_e32 v67, v67
	v_exp_f32_e32 v87, v68
	v_sub_f32_e32 v68, v95, v178
	v_exp_f32_e32 v66, v66
	v_exp_f32_e32 v89, v86
	v_sub_f32_e32 v86, v97, v178
	ds_read_b64_tr_b16 v[94:95], v92 offset:50176
	ds_read_b64_tr_b16 v[96:97], v92 offset:52736
	ds_read_b64_tr_b16 v[196:197], v92 offset:50240
	ds_read_b64_tr_b16 v[198:199], v92 offset:52800
	v_pk_mul_f32 v[64:65], v[64:65], v[66:67] op_sel_hi:[1,0]
	v_pk_mul_f32 v[62:63], v[62:63], v[66:67] op_sel_hi:[1,0]
	v_pk_mul_f32 v[60:61], v[60:61], v[66:67] op_sel_hi:[1,0]
	v_pk_mul_f32 v[58:59], v[58:59], v[66:67] op_sel_hi:[1,0]
	v_pk_mul_f32 v[56:57], v[56:57], v[66:67] op_sel_hi:[1,0]
	v_pk_mul_f32 v[54:55], v[54:55], v[66:67] op_sel_hi:[1,0]
	v_pk_mul_f32 v[52:53], v[52:53], v[66:67] op_sel_hi:[1,0]
	v_pk_mul_f32 v[50:51], v[50:51], v[66:67] op_sel_hi:[1,0]
	v_pk_mul_f32 v[48:49], v[48:49], v[66:67] op_sel_hi:[1,0]
	v_pk_mul_f32 v[46:47], v[46:47], v[66:67] op_sel_hi:[1,0]
	v_pk_mul_f32 v[44:45], v[44:45], v[66:67] op_sel_hi:[1,0]
	v_pk_mul_f32 v[42:43], v[42:43], v[66:67] op_sel_hi:[1,0]
	v_pk_mul_f32 v[40:41], v[40:41], v[66:67] op_sel_hi:[1,0]
	v_pk_mul_f32 v[38:39], v[38:39], v[66:67] op_sel_hi:[1,0]
	v_pk_mul_f32 v[36:37], v[36:37], v[66:67] op_sel_hi:[1,0]
	v_pk_mul_f32 v[34:35], v[34:35], v[66:67] op_sel_hi:[1,0]
	v_cvt_pk_bf16_f32 v192, v146, v158
	v_cvt_pk_bf16_f32 v193, v147, v160
	v_cvt_pk_bf16_f32 v194, v83, v82
	v_cvt_pk_bf16_f32 v195, v85, v84
	v_pk_mul_f32 v[32:33], v[32:33], v[66:67] op_sel_hi:[1,0]
	v_pk_mul_f32 v[30:31], v[30:31], v[66:67] op_sel_hi:[1,0]
	s_waitcnt lgkmcnt(4)
; #define LAS __attribute__((address_space(3)))
; __device__ __forceinline__ unsigned pkbf(float lo, float hi) { f32x2 v = {lo, hi}; bf16x2_t b = __builtin_convertvector(v, bf16x2_t); return __builtin_bit_cast(unsigned, b); }
; __device__ __forceinline__ s16x4 lds_tr(LAS const char* p) { return __builtin_bit_cast(s16x4, __builtin_amdgcn_ds_read_tr16_b64_v4i16((LAS s16x4*)p)); }
; __device__ __forceinline__ bf16x8 cat44(s16x4 a, s16x4 b) { return (bf16x8){a[0], a[1], a[2], a[3], b[0], b[1], b[2], b[3]}; }
; __device__ __forceinline__ f32x16 mfma32(bf16x8 a, bf16x8 b, f32x16 c) { return __builtin_amdgcn_mfma_f32_32x32x16_bf16(a, b, c, 0, 0, 0); }
; __device__ __forceinline__ float fexp2(float x) { return __builtin_amdgcn_exp2f(x); }
; __device__ __forceinline__ void fox_prompt_unit(LAS char* L, const bf16_t* P, const float* lfT, bf16_t* MIX, int b, int h, int qb, const int wv) {
;     ...
;             const float mn = fmaxf(m, mx), alpha = fexp2(m - mn); m = mn;
;             float ls = 0.f;
; #pragma unroll
;             for (int r = 0; r < 16; ++r) { s0[r] = fexp2(s0[r] - mn); s1[r] = fexp2(s1[r] - mn); ls += s0[r] + s1[r]; }
;             l = l * alpha + ls;
; #pragma unroll
;             for (int d = 0; d < 4; ++d)
; #pragma unroll
;                 for (int r = 0; r < 16; ++r) o[d][r] *= alpha;
;             bf16x8 pf[4];
;             { u32x4 w;
;               w.x = pkbf(s0[0], s0[1]); w.y = pkbf(s0[2], s0[3]); w.z = pkbf(s0[4], s0[5]); w.w = pkbf(s0[6], s0[7]); pf[0] = __builtin_bit_cast(bf16x8, w);
;               w.x = pkbf(s0[8], s0[9]); w.y = pkbf(s0[10], s0[11]); w.z = pkbf(s0[12], s0[13]); w.w = pkbf(s0[14], s0[15]); pf[1] = __builtin_bit_cast(bf16x8, w);
;               w.x = pkbf(s1[0], s1[1]); w.y = pkbf(s1[2], s1[3]); w.z = pkbf(s1[4], s1[5]); w.w = pkbf(s1[6], s1[7]); pf[2] = __builtin_bit_cast(bf16x8, w);
;               w.x = pkbf(s1[8], s1[9]); w.y = pkbf(s1[10], s1[11]); w.z = pkbf(s1[12], s1[13]); w.w = pkbf(s1[14], s1[15]); pf[3] = __builtin_bit_cast(bf16x8, w); }
; #pragma unroll
;             for (int ss = 0; ss < 4; ++ss)
; #pragma unroll
;                 for (int d = 0; d < 4; ++d) { LAS const char* vp = Vb + (16 * ss + 4 * hi + (i16 >> 2)) * AVP + (32 * d + 16 * cb + 4 * (i16 & 3)) * 2;
;                     o[d] = mfma32(cat44(lds_tr(vp), lds_tr(vp + 8 * AVP)), pf[ss], o[d]); }
	v_mfma_f32_32x32x16_bf16 v[50:65], v[200:203], v[192:195], v[50:65]
	v_mul_f32_e64 v28, v28, v66
	v_mul_f32_e64 v29, v29, v66
	v_mul_f32_e64 v26, v26, v66
	v_mul_f32_e64 v27, v27, v66
	v_pk_mul_f32 v[24:25], v[24:25], v[66:67] op_sel_hi:[1,0]
	v_pk_mul_f32 v[22:23], v[22:23], v[66:67] op_sel_hi:[1,0]
	v_pk_mul_f32 v[20:21], v[20:21], v[66:67] op_sel_hi:[1,0]
	v_pk_mul_f32 v[18:19], v[18:19], v[66:67] op_sel_hi:[1,0]
	v_mfma_f32_32x32x16_bf16 v[34:49], v[204:207], v[192:195], v[34:49]
	v_mul_f32_e64 v16, v16, v66
	v_mul_f32_e64 v17, v17, v66
	v_mul_f32_e64 v14, v14, v66
	v_mul_f32_e64 v15, v15, v66
	v_pk_mul_f32 v[12:13], v[12:13], v[66:67] op_sel_hi:[1,0]
	v_pk_mul_f32 v[10:11], v[10:11], v[66:67] op_sel_hi:[1,0]
	v_pk_mul_f32 v[8:9], v[8:9], v[66:67] op_sel_hi:[1,0]
	v_pk_mul_f32 v[6:7], v[6:7], v[66:67] op_sel_hi:[1,0]
	v_pk_mul_f32 v[4:5], v[4:5], v[66:67] op_sel_hi:[1,0]
	v_pk_mul_f32 v[2:3], v[2:3], v[66:67] op_sel_hi:[1,0]
	v_exp_f32_e32 v68, v68
	v_mfma_f32_32x32x16_bf16 v[18:33], v[208:211], v[192:195], v[18:33]
	v_exp_f32_e32 v86, v86
	v_sub_f32_e32 v71, v71, v178
	v_exp_f32_e32 v88, v71
	v_exp_f32_e32 v0, v0
	v_sub_f32_e32 v71, v73, v178
	v_exp_f32_e32 v90, v71
	v_mfma_f32_32x32x16_bf16 v[2:17], v[212:215], v[192:195], v[2:17]
	v_cvt_pk_bf16_f32 v192, v190, v70
	v_cvt_pk_bf16_f32 v193, v91, v72
	v_cvt_pk_bf16_f32 v194, v87, v68
	v_cvt_pk_bf16_f32 v195, v89, v86
	v_sub_f32_e32 v71, v74, v178
	v_exp_f32_e32 v93, v71
	v_mfma_f32_32x32x16_bf16 v[50:65], v[216:219], v[192:195], v[50:65]
	v_add_f32_e32 v159, v146, v163
	v_add_f32_e32 v83, v83, v67
	v_sub_f32_e32 v71, v76, v178
	v_sub_f32_e32 v76, v79, v178
	v_sub_f32_e32 v73, v75, v178
	v_sub_f32_e32 v75, v78, v178
	v_mfma_f32_32x32x16_bf16 v[34:49], v[220:223], v[192:195], v[34:49]
	v_exp_f32_e32 v148, v76
	v_sub_f32_e32 v76, v81, v178
	v_exp_f32_e32 v75, v75
	v_add_f32_e32 v161, v147, v179
	v_exp_f32_e32 v147, v71
	v_add_f32_e32 v71, v190, v93
	v_mfma_f32_32x32x16_bf16 v[18:33], v[224:227], v[192:195], v[18:33]
	v_cvt_pk_bf16_f32 v190, v163, v0
	v_add_f32_e32 v85, v85, v69
	v_cvt_pk_bf16_f32 v191, v179, v162
	v_exp_f32_e32 v74, v73
	v_add_f32_e32 v73, v91, v147
	v_mfma_f32_32x32x16_bf16 v[2:17], v[228:231], v[192:195], v[2:17]
	v_cvt_pk_bf16_f32 v192, v67, v88
	v_sub_f32_e32 v67, v77, v178
	v_exp_f32_e32 v146, v67
	v_sub_f32_e32 v67, v80, v178
	v_pk_add_f32 v[80:81], v[158:159], v[0:1]
	v_exp_f32_e32 v67, v67
	v_pk_add_f32 v[80:81], v[80:81], v[80:81] op_sel_hi:[0,1]
	v_mov_b32_e32 v163, v81
	v_pk_add_f32 v[80:81], v[160:161], v[162:163]
	v_cvt_pk_bf16_f32 v193, v69, v90
	v_pk_add_f32 v[80:81], v[80:81], v[80:81] op_sel_hi:[0,1]
	v_add_f32_e32 v69, v87, v75
	v_add_f32_e32 v87, v89, v67
	v_mov_b32_e32 v89, v81
	v_mfma_f32_32x32x16_bf16 v[50:65], v[232:235], v[190:193], v[50:65]
	v_add_f32_e64 v80, v82, v88
	v_add_f32_e64 v81, v83, v89
	v_pk_add_f32 v[80:81], v[80:81], v[80:81] op_sel_hi:[0,1]
	v_mov_b32_e32 v91, v81
	v_pk_add_f32 v[80:81], v[84:85], v[90:91]
	v_mfma_f32_32x32x16_bf16 v[34:49], v[236:239], v[190:193], v[34:49]
	v_exp_f32_e32 v194, v76
	v_pk_add_f32 v[84:85], v[80:81], v[80:81] op_sel_hi:[0,1]
	v_mfma_f32_32x32x16_bf16 v[2:17], v[240:243], v[190:193], v[2:17]
	v_cvt_pk_bf16_f32 v78, v75, v148
	v_mov_b32_e32 v75, v85
	v_add_f32_e64 v70, v70, v74
	v_add_f32_e64 v71, v71, v75
	v_cvt_pk_bf16_f32 v77, v147, v146
	v_pk_add_f32 v[70:71], v[70:71], v[70:71] op_sel_hi:[0,1]
	v_mov_b32_e32 v147, v71
	v_cvt_pk_bf16_f32 v76, v93, v74
	v_mfma_f32_32x32x16_bf16 v[18:33], v[244:247], v[190:193], v[18:33]
	ds_read_b64_tr_b16 v[80:81], v92 offset:50304
	ds_read_b64_tr_b16 v[82:83], v92 offset:52864
	v_pk_add_f32 v[74:75], v[72:73], v[146:147]
	ds_read_b64_tr_b16 v[70:71], v92 offset:50368
	ds_read_b64_tr_b16 v[72:73], v92 offset:52928
	v_cvt_pk_bf16_f32 v79, v67, v194
	v_pk_add_f32 v[74:75], v[74:75], v[74:75] op_sel_hi:[0,1]
	v_mov_b32_e32 v149, v75
	s_waitcnt lgkmcnt(4)
	v_mfma_f32_32x32x16_bf16 v[50:65], v[94:97], v[76:79], v[50:65]
	v_add_f32_e64 v68, v68, v148
	v_add_f32_e64 v69, v69, v149
	v_pk_add_f32 v[68:69], v[68:69], v[68:69] op_sel_hi:[0,1]
	v_mov_b32_e32 v195, v69
	v_pk_add_f32 v[68:69], v[86:87], v[194:195]
	s_nop 0
	v_add_f32_e32 v0, v68, v69
	s_waitcnt lgkmcnt(4)
	v_mfma_f32_32x32x16_bf16 v[34:49], v[196:199], v[76:79], v[34:49]
	v_fmac_f32_e32 v0, v177, v66
	v_mov_b32_e32 v158, v178
	v_mov_b32_e32 v177, v0
	s_waitcnt lgkmcnt(2)
	v_mfma_f32_32x32x16_bf16 v[18:33], v[80:83], v[76:79], v[18:33]
	s_waitcnt lgkmcnt(0)
	v_mfma_f32_32x32x16_bf16 v[2:17], v[70:73], v[76:79], v[2:17]
